# first row phase: g_pre / shift / scale vector loads of both rows issued ahead with counted vmcnt (store deferral dropped)
# speedup vs baseline: 1.0152x; 1.0064x over previous
.LBB0_35:
	s_or_b64 exec, exec, s[12:13]
	v_mov_b32_e32 v3, v0
	v_lshl_add_u64 v[2:3], v[4:5], 0, v[2:3]
	global_load_dwordx4 v[18:21], v[2:3], off nt
	global_load_dwordx4 v[10:13], v[2:3], off offset:1024 nt
	global_load_dwordx4 v[6:9], v[2:3], off offset:2048 nt
	s_nop 0
	global_load_dwordx4 v[2:5], v[2:3], off offset:3072 nt
	v_ashrrev_i32_e32 v45, 12, v52
	s_waitcnt vmcnt(7)
	v_mov_b32_e32 v62, v31
	s_waitcnt vmcnt(6)
	v_mov_b32_e32 v63, v27
	s_waitcnt vmcnt(5)
	v_mov_b32_e32 v70, v23
	s_waitcnt vmcnt(4)
	v_mov_b32_e32 v71, v15
	v_mov_b32_e32 v52, v30
	v_mov_b32_e32 v53, v26
	v_mov_b32_e32 v68, v22
	v_mov_b32_e32 v69, v14
	v_add_u32_e32 v96, 1, v45
	v_pk_mul_f32 v[62:63], v[62:63], v[62:63]
	v_pk_mul_f32 v[70:71], v[70:71], v[70:71]
	v_mov_b32_e32 v64, v32
	v_mov_b32_e32 v65, v28
	v_mov_b32_e32 v72, v24
	v_mov_b32_e32 v73, v16
	v_cndmask_b32_e64 v45, v96, 0, s[0:1]
	v_pk_fma_f32 v[52:53], v[52:53], v[52:53], v[62:63]
	v_pk_fma_f32 v[62:63], v[68:69], v[68:69], v[70:71]
	v_mov_b32_e32 v74, v25
	v_mov_b32_e32 v75, v17
	v_pk_fma_f32 v[52:53], v[64:65], v[64:65], v[52:53]
	v_pk_fma_f32 v[62:63], v[72:73], v[72:73], v[62:63]
	v_mul_hi_i32_i24_e32 v65, 0x3000, v45
	v_mul_i32_i24_e32 v64, 0x3000, v45
	v_pk_fma_f32 v[70:71], v[74:75], v[74:75], v[62:63]
	v_lshl_add_u64 v[62:63], s[30:31], 0, v[64:65]
	s_mov_b64 s[40:41], 0x1000
	v_mov_b32_e32 v66, v33
	v_mov_b32_e32 v67, v29
	v_mov_b32_e32 v43, v0
	v_lshl_add_u64 v[72:73], v[62:63], 0, s[40:41]
	v_pk_fma_f32 v[52:53], v[66:67], v[66:67], v[52:53]
	v_lshl_add_u64 v[74:75], v[62:63], 0, v[42:43]
	v_lshl_add_u64 v[66:67], v[72:73], 0, v[42:43]
	v_lshl_add_u64 v[242:243], v[72:73], 0, v[42:43]
	global_load_dwordx4 v[152:155], v[36:37], off
	global_load_dwordx4 v[156:159], v[74:75], off
	global_load_dwordx4 v[160:163], v[242:243], off
	global_load_dwordx4 v[164:167], v[36:37], off offset:1024
	global_load_dwordx4 v[168:171], v[242:243], off offset:1024
	global_load_dwordx4 v[234:237], v[74:75], off offset:1024
	global_load_dwordx4 v[238:241], v[36:37], off offset:2048
	global_load_dwordx4 v[250:253], v[242:243], off offset:2048
	s_nop 0
	v_mov_b32_e32 v77, v52
	v_mov_b32_e32 v79, v70
	s_mov_b32 s0, 0x3a800000
	s_mov_b32 s12, 0x800000
	v_mov_b32_e32 v45, v0
	v_mov_b32_e32 v49, v0
	s_add_i32 s43, s43, s2
	s_mov_b32 s98, 0x800000
	s_cmpk_gt_i32 s43, 0x13ff
	s_waitcnt vmcnt(11)
	v_mov_b32_e32 v82, v19
	s_waitcnt vmcnt(10)
	v_mov_b32_e32 v83, v11
	v_mov_b32_e32 v80, v18
	v_mov_b32_e32 v81, v10
	s_waitcnt vmcnt(9)
	v_mov_b32_e32 v90, v7
	s_waitcnt vmcnt(8)
	v_mov_b32_e32 v91, v3
	v_pk_mul_f32 v[82:83], v[82:83], v[82:83]
	v_mov_b32_e32 v84, v20
	v_mov_b32_e32 v85, v12
	v_mov_b32_e32 v88, v6
	v_mov_b32_e32 v89, v2
	v_pk_mul_f32 v[90:91], v[90:91], v[90:91]
	v_pk_fma_f32 v[80:81], v[80:81], v[80:81], v[82:83]
	v_mov_b32_e32 v86, v21
	v_mov_b32_e32 v87, v13
	v_mov_b32_e32 v92, v8
	v_mov_b32_e32 v93, v4
	v_pk_fma_f32 v[82:83], v[88:89], v[88:89], v[90:91]
	v_pk_fma_f32 v[80:81], v[84:85], v[84:85], v[80:81]
	v_mov_b32_e32 v94, v9
	v_mov_b32_e32 v95, v5
	v_pk_fma_f32 v[82:83], v[92:93], v[92:93], v[82:83]
	v_pk_fma_f32 v[80:81], v[86:87], v[86:87], v[80:81]
	v_pk_fma_f32 v[82:83], v[94:95], v[94:95], v[82:83]
	v_mov_b32_e32 v76, v80
	v_mov_b32_e32 v52, v81
	v_mov_b32_e32 v78, v82
	v_pk_add_f32 v[52:53], v[76:77], v[52:53]
	v_mov_b32_e32 v70, v83
	v_pk_add_f32 v[52:53], v[52:53], v[78:79]
	v_lshlrev_b64 v[76:77], 11, v[40:41]
	v_pk_add_f32 v[52:53], v[52:53], v[70:71]
	v_lshl_add_u64 v[76:77], v[38:39], 0, v[76:77]
	v_add_u32_e32 v40, s42, v40
	s_nop 1
	v_add_f32_dpp v52, v52, v52 quad_perm:[1,0,3,2] row_mask:0xf bank_mask:0xf
	v_add_f32_dpp v53, v53, v53 quad_perm:[1,0,3,2] row_mask:0xf bank_mask:0xf
	s_waitcnt vmcnt(8)
	s_waitcnt vmcnt(5)
	v_pk_add_f32 v[66:67], v[160:161], 1.0 op_sel_hi:[1,0]
	v_pk_add_f32 v[68:69], v[162:163], 1.0 op_sel_hi:[1,0]
	s_nop 1
	v_add_f32_dpp v52, v52, v52 quad_perm:[2,3,0,1] row_mask:0xf bank_mask:0xf
	v_add_f32_dpp v53, v53, v53 quad_perm:[2,3,0,1] row_mask:0xf bank_mask:0xf
	s_nop 1
	v_add_f32_dpp v52, v52, v52 row_half_mirror row_mask:0xf bank_mask:0xf
	v_add_f32_dpp v53, v53, v53 row_half_mirror row_mask:0xf bank_mask:0xf
	s_nop 1
	v_add_f32_dpp v52, v52, v52 row_mirror row_mask:0xf bank_mask:0xf
	v_add_f32_dpp v53, v53, v53 row_mirror row_mask:0xf bank_mask:0xf
	v_mov_b32_e32 v70, v52
	v_mov_b32_e32 v71, v53
	s_nop 1
	v_permlane16_swap_b32_e32 v52, v70
	v_permlane16_swap_b32_e32 v53, v71
	v_pk_add_f32 v[52:53], v[52:53], v[70:71]
	v_mov_b32_e32 v70, v52
	v_mov_b32_e32 v71, v53
	s_nop 1
	v_permlane32_swap_b32_e32 v52, v70
	v_permlane32_swap_b32_e32 v53, v71
	v_pk_add_f32 v[52:53], v[52:53], v[70:71]
	s_nop 0
	v_pk_fma_f32 v[52:53], v[52:53], s[0:1], v[148:149] op_sel_hi:[1,0,0]
	v_lshl_add_u64 v[70:71], v[72:73], 0, v[44:45]
	v_mul_f32_e32 v41, 0x4b800000, v53
	v_cmp_gt_f32_e64 s[0:1], s12, v53
	s_nop 1
	v_cndmask_b32_e64 v41, v53, v41, s[0:1]
	v_rsq_f32_e32 v41, v41
	s_nop 0
	v_mul_f32_e32 v47, 0x45800000, v41
	v_cndmask_b32_e64 v78, v41, v47, s[0:1]
	v_pk_mul_f32 v[30:31], v[30:31], v[78:79] op_sel_hi:[1,0]
	v_pk_mul_f32 v[32:33], v[32:33], v[78:79] op_sel_hi:[1,0]
	v_pk_mul_f32 v[30:31], v[152:153], v[30:31]
	v_pk_mul_f32 v[32:33], v[154:155], v[32:33]
	v_pk_fma_f32 v[30:31], v[66:67], v[30:31], v[156:157]
	v_pk_fma_f32 v[32:33], v[32:33], v[68:69], v[158:159]
	v_cvt_pk_bf16_f32 v30, v30, v31
	v_cvt_pk_bf16_f32 v31, v32, v33
	global_store_dwordx2 v[76:77], v[30:31], off
	global_load_dwordx4 v[152:155], v[74:75], off offset:2048
	global_load_dwordx4 v[156:159], v[36:37], off offset:3072
	global_load_dwordx4 v[160:163], v[242:243], off offset:3072
	s_nop 0
	v_pk_mul_f32 v[26:27], v[26:27], v[78:79] op_sel_hi:[1,0]
	v_pk_mul_f32 v[28:29], v[28:29], v[78:79] op_sel_hi:[1,0]
	v_mov_b32_e32 v47, v0
	v_lshl_add_u64 v[66:67], v[72:73], 0, v[46:47]
	v_pk_mul_f32 v[22:23], v[22:23], v[78:79] op_sel_hi:[1,0]
	v_pk_mul_f32 v[24:25], v[24:25], v[78:79] op_sel_hi:[1,0]
	v_pk_mul_f32 v[14:15], v[14:15], v[78:79] op_sel_hi:[1,0]
	v_pk_mul_f32 v[16:17], v[16:17], v[78:79] op_sel_hi:[1,0]
	v_cndmask_b32_e64 v41, v96, 0, vcc
	v_cmp_gt_f32_e32 vcc, s12, v52
	s_waitcnt vmcnt(8)
	v_pk_mul_f32 v[26:27], v[26:27], v[164:165]
	s_waitcnt vmcnt(7)
	v_pk_add_f32 v[30:31], v[168:169], 1.0 op_sel_hi:[1,0]
	v_pk_mul_f32 v[28:29], v[28:29], v[166:167]
	v_pk_add_f32 v[32:33], v[170:171], 1.0 op_sel_hi:[1,0]
	s_waitcnt vmcnt(6)
	v_pk_fma_f32 v[26:27], v[26:27], v[30:31], v[234:235]
	v_pk_fma_f32 v[28:29], v[28:29], v[32:33], v[236:237]
	v_cvt_pk_bf16_f32 v26, v26, v27
	v_cvt_pk_bf16_f32 v27, v28, v29
	global_store_dwordx2 v[76:77], v[26:27], off offset:512
	global_load_dwordx4 v[164:167], v[74:75], off offset:3072
	s_nop 0
	v_lshl_add_u64 v[62:63], v[72:73], 0, v[48:49]
	s_waitcnt vmcnt(7)
	v_pk_mul_f32 v[22:23], v[22:23], v[238:239]
	s_waitcnt vmcnt(6)
	v_pk_add_f32 v[26:27], v[250:251], 1.0 op_sel_hi:[1,0]
	v_pk_mul_f32 v[24:25], v[24:25], v[240:241]
	v_pk_add_f32 v[28:29], v[252:253], 1.0 op_sel_hi:[1,0]
	s_waitcnt vmcnt(4)
	v_pk_fma_f32 v[22:23], v[22:23], v[26:27], v[152:153]
	v_pk_fma_f32 v[24:25], v[24:25], v[28:29], v[154:155]
	v_cvt_pk_bf16_f32 v22, v22, v23
	v_cvt_pk_bf16_f32 v23, v24, v25
	global_store_dwordx2 v[76:77], v[22:23], off offset:1024
	s_nop 0
	v_mul_hi_i32_i24_e32 v59, 0x3000, v41
	v_mul_i32_i24_e32 v58, 0x3000, v41
	v_lshl_add_u64 v[58:59], s[30:31], 0, v[58:59]
	v_lshl_add_u64 v[60:61], v[58:59], 0, s[40:41]
	v_lshl_add_u64 v[62:63], v[60:61], 0, v[42:43]
	s_waitcnt vmcnt(4)
	v_pk_mul_f32 v[14:15], v[14:15], v[156:157]
	s_waitcnt vmcnt(3)
	v_pk_add_f32 v[22:23], v[160:161], 1.0 op_sel_hi:[1,0]
	v_pk_mul_f32 v[16:17], v[16:17], v[158:159]
	v_pk_add_f32 v[24:25], v[162:163], 1.0 op_sel_hi:[1,0]
	s_waitcnt vmcnt(1)
	v_pk_fma_f32 v[14:15], v[14:15], v[22:23], v[164:165]
	v_pk_fma_f32 v[16:17], v[16:17], v[24:25], v[166:167]
	v_cvt_pk_bf16_f32 v14, v14, v15
	v_cvt_pk_bf16_f32 v15, v16, v17
	global_store_dwordx2 v[76:77], v[14:15], off offset:1536
	v_lshl_add_u64 v[242:243], v[60:61], 0, v[42:43]
	v_lshl_add_u64 v[254:255], v[58:59], 0, v[42:43]
	global_load_dwordx4 v[152:155], v[36:37], off
	global_load_dwordx4 v[156:159], v[242:243], off
	global_load_dwordx4 v[160:163], v[254:255], off
	global_load_dwordx4 v[164:167], v[36:37], off offset:1024
	global_load_dwordx4 v[168:171], v[242:243], off offset:1024
	global_load_dwordx4 v[234:237], v[254:255], off offset:1024
	global_load_dwordx4 v[238:241], v[36:37], off offset:2048
	global_load_dwordx4 v[250:253], v[242:243], off offset:2048
	s_nop 0
	v_lshl_add_u64 v[30:31], v[58:59], 0, v[42:43]
	v_mul_f32_e32 v32, 0x4b800000, v52
	v_cndmask_b32_e32 v32, v52, v32, vcc
	v_rsq_f32_e32 v41, v32
	v_lshlrev_b64 v[32:33], 11, v[50:51]
	v_lshl_add_u64 v[32:33], v[38:39], 0, v[32:33]
	v_lshl_add_u64 v[50:51], v[60:61], 0, v[44:45]
	v_mul_f32_e32 v43, 0x45800000, v41
	v_cndmask_b32_e32 v52, v41, v43, vcc
	v_pk_mul_f32 v[18:19], v[18:19], v[52:53] op_sel_hi:[1,0]
	v_pk_mul_f32 v[20:21], v[20:21], v[52:53] op_sel_hi:[1,0]
	v_pk_mul_f32 v[10:11], v[10:11], v[52:53] op_sel_hi:[1,0]
	v_pk_mul_f32 v[12:13], v[12:13], v[52:53] op_sel_hi:[1,0]
	v_pk_mul_f32 v[6:7], v[6:7], v[52:53] op_sel_hi:[1,0]
	v_pk_mul_f32 v[8:9], v[8:9], v[52:53] op_sel_hi:[1,0]
	v_pk_mul_f32 v[2:3], v[2:3], v[52:53] op_sel_hi:[1,0]
	v_pk_mul_f32 v[4:5], v[4:5], v[52:53] op_sel_hi:[1,0]
	s_waitcnt vmcnt(8)
	s_waitcnt vmcnt(7)
	v_pk_mul_f32 v[14:15], v[152:153], v[18:19]
	s_waitcnt vmcnt(6)
	v_pk_add_f32 v[18:19], v[156:157], 1.0 op_sel_hi:[1,0]
	v_pk_mul_f32 v[16:17], v[154:155], v[20:21]
	v_pk_add_f32 v[20:21], v[158:159], 1.0 op_sel_hi:[1,0]
	s_waitcnt vmcnt(5)
	v_pk_fma_f32 v[14:15], v[18:19], v[14:15], v[160:161]
	v_pk_fma_f32 v[16:17], v[16:17], v[20:21], v[162:163]
	v_cvt_pk_bf16_f32 v14, v14, v15
	v_cvt_pk_bf16_f32 v15, v16, v17
	global_store_dwordx2 v[32:33], v[14:15], off
	global_load_dwordx4 v[152:155], v[254:255], off offset:2048
	global_load_dwordx4 v[156:159], v[36:37], off offset:3072
	global_load_dwordx4 v[160:163], v[242:243], off offset:3072
	s_nop 0
	v_lshl_add_u64 v[26:27], v[60:61], 0, v[46:47]
	s_waitcnt vmcnt(8)
	v_pk_mul_f32 v[10:11], v[10:11], v[164:165]
	s_waitcnt vmcnt(7)
	v_pk_add_f32 v[14:15], v[168:169], 1.0 op_sel_hi:[1,0]
	v_pk_mul_f32 v[12:13], v[12:13], v[166:167]
	v_pk_add_f32 v[16:17], v[170:171], 1.0 op_sel_hi:[1,0]
	s_waitcnt vmcnt(6)
	v_pk_fma_f32 v[10:11], v[10:11], v[14:15], v[234:235]
	v_pk_fma_f32 v[12:13], v[12:13], v[16:17], v[236:237]
	v_cvt_pk_bf16_f32 v10, v10, v11
	v_cvt_pk_bf16_f32 v11, v12, v13
	global_store_dwordx2 v[32:33], v[10:11], off offset:512
	global_load_dwordx4 v[164:167], v[254:255], off offset:3072
	s_nop 0
	v_lshl_add_u64 v[22:23], v[60:61], 0, v[48:49]
	s_waitcnt vmcnt(7)
	v_pk_mul_f32 v[6:7], v[6:7], v[238:239]
	s_waitcnt vmcnt(6)
	v_pk_add_f32 v[10:11], v[250:251], 1.0 op_sel_hi:[1,0]
	v_pk_mul_f32 v[8:9], v[8:9], v[240:241]
	v_pk_add_f32 v[12:13], v[252:253], 1.0 op_sel_hi:[1,0]
	s_waitcnt vmcnt(4)
	v_pk_fma_f32 v[6:7], v[6:7], v[10:11], v[152:153]
	v_pk_fma_f32 v[8:9], v[8:9], v[12:13], v[154:155]
	v_cvt_pk_bf16_f32 v6, v6, v7
	v_cvt_pk_bf16_f32 v7, v8, v9
	global_store_dwordx2 v[32:33], v[6:7], off offset:1024
	s_nop 0
	s_waitcnt vmcnt(4)
	v_pk_mul_f32 v[2:3], v[2:3], v[156:157]
	s_waitcnt vmcnt(3)
	v_pk_add_f32 v[6:7], v[160:161], 1.0 op_sel_hi:[1,0]
	v_pk_mul_f32 v[4:5], v[4:5], v[158:159]
	v_pk_add_f32 v[8:9], v[162:163], 1.0 op_sel_hi:[1,0]
	s_waitcnt vmcnt(1)
	v_pk_fma_f32 v[2:3], v[2:3], v[6:7], v[164:165]
	v_pk_fma_f32 v[4:5], v[4:5], v[8:9], v[166:167]
	v_cvt_pk_bf16_f32 v2, v2, v3
	v_cvt_pk_bf16_f32 v3, v4, v5
	global_store_dwordx2 v[32:33], v[2:3], off offset:1536
	s_cbranch_scc1 .LBB0_44

.LBB0_182:
	s_waitcnt vmcnt(6)
	v_mov_b32_e32 v86, v26
	v_mov_b32_e32 v87, v30
	v_pk_mul_f32 v[86:87], v[86:87], v[86:87]
	v_mov_b32_e32 v88, v27
	v_mov_b32_e32 v89, v31
	v_pk_fma_f32 v[86:87], v[88:89], v[88:89], v[86:87]
	v_mov_b32_e32 v88, v28
	v_mov_b32_e32 v89, v32
	v_pk_fma_f32 v[86:87], v[88:89], v[88:89], v[86:87]
	v_mov_b32_e32 v88, v29
	v_mov_b32_e32 v89, v33
	v_pk_fma_f32 v[86:87], v[88:89], v[88:89], v[86:87]
	s_waitcnt vmcnt(4)
	v_mov_b32_e32 v88, v18
	v_mov_b32_e32 v89, v22
	v_pk_mul_f32 v[88:89], v[88:89], v[88:89]
	v_mov_b32_e32 v90, v19
	v_mov_b32_e32 v91, v23
	v_pk_fma_f32 v[88:89], v[90:91], v[90:91], v[88:89]
	v_mov_b32_e32 v90, v20
	v_mov_b32_e32 v91, v24
	v_pk_fma_f32 v[88:89], v[90:91], v[90:91], v[88:89]
	v_mov_b32_e32 v90, v21
	v_mov_b32_e32 v91, v25
	v_pk_fma_f32 v[88:89], v[90:91], v[90:91], v[88:89]
	v_add_f32_e32 v41, v86, v87
	v_add_f32_e32 v41, v89, v41
	v_readlane_b32 s0, v246, 41
	v_add_f32_e32 v41, v88, v41
	v_mov_b64_e32 v[88:89], s[30:31]
	v_add_u32_e32 v39, s0, v39
	v_mad_i64_i32 v[88:89], s[0:1], v39, s16, v[88:89]
	s_mov_b64 s[0:1], 0x1000
	s_nop 0
	v_lshl_add_u64 v[90:91], v[88:89], 0, s[0:1]
	v_mov_b32_e32 v79, v0
	v_lshl_add_u64 v[100:101], v[90:91], 0, v[78:79]
	v_lshl_add_u64 v[88:89], v[88:89], 0, v[78:79]
	v_lshl_add_u64 v[242:243], v[90:91], 0, v[78:79]
	global_load_dwordx4 v[152:155], v[48:49], off
	global_load_dwordx4 v[156:159], v[88:89], off
	global_load_dwordx4 v[160:163], v[242:243], off
	global_load_dwordx4 v[164:167], v[48:49], off offset:1024
	global_load_dwordx4 v[168:171], v[88:89], off offset:1024
	global_load_dwordx4 v[234:237], v[242:243], off offset:1024
	global_load_dwordx4 v[238:241], v[48:49], off offset:2048
	global_load_dwordx4 v[250:253], v[88:89], off offset:2048
	s_nop 0
	v_mov_b32_e32 v77, v0
	v_mov_b32_e32 v75, v0
	v_mov_b32_e32 v73, v0
	s_nop 1
	v_add_f32_dpp v41, v41, v41 quad_perm:[1,0,3,2] row_mask:0xf bank_mask:0xf
	s_nop 1
	s_nop 1
	v_add_f32_dpp v41, v41, v41 quad_perm:[2,3,0,1] row_mask:0xf bank_mask:0xf
	s_nop 1
	s_nop 1
	v_add_f32_dpp v41, v41, v41 row_half_mirror row_mask:0xf bank_mask:0xf
	s_nop 1
	s_nop 1
	v_add_f32_dpp v41, v41, v41 row_mirror row_mask:0xf bank_mask:0xf
	s_nop 1
	v_mov_b32_e32 v53, v41
	s_nop 1
	v_permlane16_swap_b32_e32 v41, v53
	v_add_f32_e32 v41, v41, v53
	s_nop 1
	v_mov_b32_e32 v43, v41
	s_nop 1
	v_permlane32_swap_b32_e32 v41, v43
	v_add_f32_e32 v41, v41, v43
	v_fmamk_f32 v41, v41, 0x3a800000, v148
	v_cmp_gt_f32_e32 vcc, s98, v41
	v_mul_f32_e32 v43, 0x4b800000, v41
	s_nop 0
	v_cndmask_b32_e32 v41, v41, v43, vcc
	v_rsq_f32_e32 v41, v41
	s_nop 0
	v_mul_f32_e32 v43, 0x45800000, v41
	v_cndmask_b32_e32 v86, v41, v43, vcc
	v_pk_mul_f32 v[30:31], v[30:31], v[86:87] op_sel_hi:[1,0]
	v_pk_mul_f32 v[26:27], v[26:27], v[86:87] op_sel_hi:[1,0]
	s_waitcnt vmcnt(8)
	s_waitcnt vmcnt(7)
	v_pk_mul_f32 v[30:31], v[152:153], v[30:31]
	s_waitcnt vmcnt(5)
	v_pk_add_f32 v[92:93], v[160:161], 1.0 op_sel_hi:[1,0]
	v_pk_mul_f32 v[28:29], v[28:29], v[86:87] op_sel_hi:[1,0]
	v_pk_fma_f32 v[30:31], v[92:93], v[30:31], v[156:157]
	v_pk_mul_f32 v[22:23], v[22:23], v[86:87] op_sel_hi:[1,0]
	v_cvt_pk_bf16_f32 v92, v30, v31
	v_pk_mul_f32 v[30:31], v[32:33], v[86:87] op_sel_hi:[1,0]
	v_pk_add_f32 v[32:33], v[162:163], 1.0 op_sel_hi:[1,0]
	v_pk_mul_f32 v[30:31], v[154:155], v[30:31]
	v_pk_mul_f32 v[24:25], v[24:25], v[86:87] op_sel_hi:[1,0]
	v_pk_fma_f32 v[30:31], v[30:31], v[32:33], v[158:159]
	v_lshl_add_u64 v[32:33], v[90:91], 0, v[76:77]
	v_cvt_pk_bf16_f32 v93, v30, v31
	v_lshl_add_u64 v[30:31], v[84:85], 1, v[50:51]
	global_store_dwordx2 v[30:31], v[92:93], off
	global_load_dwordx4 v[152:155], v[242:243], off offset:2048
	global_load_dwordx4 v[156:159], v[48:49], off offset:3072
	global_load_dwordx4 v[160:163], v[88:89], off offset:3072
	s_nop 0
	v_pk_mul_f32 v[18:19], v[18:19], v[86:87] op_sel_hi:[1,0]
	v_pk_mul_f32 v[20:21], v[20:21], v[86:87] op_sel_hi:[1,0]
	s_waitcnt vmcnt(8)
	v_pk_mul_f32 v[26:27], v[26:27], v[164:165]
	v_pk_mul_f32 v[28:29], v[28:29], v[166:167]
	s_waitcnt vmcnt(6)
	v_pk_add_f32 v[32:33], v[234:235], 1.0 op_sel_hi:[1,0]
	s_nop 0
	v_pk_fma_f32 v[26:27], v[26:27], v[32:33], v[168:169]
	v_pk_add_f32 v[32:33], v[236:237], 1.0 op_sel_hi:[1,0]
	v_cvt_pk_bf16_f32 v26, v26, v27
	v_pk_fma_f32 v[28:29], v[28:29], v[32:33], v[170:171]
	v_lshl_add_u64 v[32:33], v[90:91], 0, v[74:75]
	v_cvt_pk_bf16_f32 v27, v28, v29
	global_store_dwordx2 v[30:31], v[26:27], off offset:512
	global_load_dwordx4 v[164:167], v[242:243], off offset:3072
	s_nop 0
	v_lshl_add_u64 v[32:33], v[90:91], 0, v[72:73]
	s_waitcnt vmcnt(7)
	v_pk_mul_f32 v[22:23], v[22:23], v[238:239]
	v_pk_mul_f32 v[24:25], v[24:25], v[240:241]
	s_waitcnt vmcnt(4)
	v_pk_add_f32 v[26:27], v[152:153], 1.0 op_sel_hi:[1,0]
	s_nop 0
	v_pk_fma_f32 v[22:23], v[22:23], v[26:27], v[250:251]
	v_pk_add_f32 v[26:27], v[154:155], 1.0 op_sel_hi:[1,0]
	v_cvt_pk_bf16_f32 v22, v22, v23
	v_pk_fma_f32 v[24:25], v[24:25], v[26:27], v[252:253]
	s_nop 0
	v_cvt_pk_bf16_f32 v23, v24, v25
	global_store_dwordx2 v[30:31], v[22:23], off offset:1024
	s_nop 0
	s_nop 0
	s_waitcnt vmcnt(4)
	v_pk_mul_f32 v[18:19], v[18:19], v[156:157]
	v_pk_mul_f32 v[20:21], v[20:21], v[158:159]
	s_waitcnt vmcnt(1)
	v_pk_add_f32 v[22:23], v[164:165], 1.0 op_sel_hi:[1,0]
	s_nop 0
	v_pk_fma_f32 v[18:19], v[18:19], v[22:23], v[160:161]
	v_pk_add_f32 v[22:23], v[166:167], 1.0 op_sel_hi:[1,0]
	v_cvt_pk_bf16_f32 v18, v18, v19
	v_pk_fma_f32 v[20:21], v[20:21], v[22:23], v[162:163]
	s_nop 0
	v_cvt_pk_bf16_f32 v19, v20, v21
	global_store_dwordx2 v[30:31], v[18:19], off offset:1536
	s_and_b64 vcc, exec, s[40:41]
	v_cndmask_b32_e64 v19, v37, 0, s[42:43]
	s_cbranch_vccnz .LBB0_181

.LBB0_184:
	s_waitcnt vmcnt(2)
	v_mov_b32_e32 v20, v10
	v_mov_b32_e32 v21, v14
	v_pk_mul_f32 v[20:21], v[20:21], v[20:21]
	v_mov_b32_e32 v22, v11
	v_mov_b32_e32 v23, v15
	v_pk_fma_f32 v[20:21], v[22:23], v[22:23], v[20:21]
	v_mov_b32_e32 v22, v12
	v_mov_b32_e32 v23, v16
	v_pk_fma_f32 v[20:21], v[22:23], v[22:23], v[20:21]
	v_mov_b32_e32 v22, v13
	v_mov_b32_e32 v23, v17
	v_pk_fma_f32 v[20:21], v[22:23], v[22:23], v[20:21]
	s_waitcnt vmcnt(0)
	v_mov_b32_e32 v22, v2
	v_mov_b32_e32 v23, v6
	v_pk_mul_f32 v[22:23], v[22:23], v[22:23]
	v_mov_b32_e32 v24, v3
	v_mov_b32_e32 v25, v7
	v_pk_fma_f32 v[22:23], v[24:25], v[24:25], v[22:23]
	v_mov_b32_e32 v24, v4
	v_mov_b32_e32 v25, v8
	v_add_f32_e32 v18, v20, v21
	v_pk_fma_f32 v[22:23], v[24:25], v[24:25], v[22:23]
	v_mov_b32_e32 v24, v5
	v_mov_b32_e32 v25, v9
	v_pk_fma_f32 v[22:23], v[24:25], v[24:25], v[22:23]
	v_add_f32_e32 v18, v23, v18
	v_add_f32_e32 v18, v22, v18
	v_readlane_b32 s0, v246, 41
	v_mov_b32_e32 v79, v0
	v_mov_b32_e32 v77, v0
	v_add_u32_e32 v19, s0, v19
	s_nop 1
	v_add_f32_dpp v18, v18, v18 quad_perm:[1,0,3,2] row_mask:0xf bank_mask:0xf
	v_mov_b32_e32 v75, v0
	v_mov_b32_e32 v73, v0
	s_nop 1
	v_add_f32_dpp v18, v18, v18 quad_perm:[2,3,0,1] row_mask:0xf bank_mask:0xf
	s_nop 1
	s_nop 1
	v_add_f32_dpp v18, v18, v18 row_half_mirror row_mask:0xf bank_mask:0xf
	s_nop 1
	s_nop 1
	v_add_f32_dpp v18, v18, v18 row_mirror row_mask:0xf bank_mask:0xf
	s_nop 1
	v_mov_b32_e32 v21, v18
	s_nop 1
	v_permlane16_swap_b32_e32 v18, v21
	v_add_f32_e32 v18, v18, v21
	s_nop 1
	v_mov_b32_e32 v20, v18
	s_nop 1
	v_permlane32_swap_b32_e32 v18, v20
	v_add_f32_e32 v18, v18, v20
	v_fmamk_f32 v18, v18, 0x3a800000, v148
	v_cmp_gt_f32_e32 vcc, s98, v18
	v_mul_f32_e32 v20, 0x4b800000, v18
	s_nop 0
	v_cndmask_b32_e32 v18, v18, v20, vcc
	v_rsq_f32_e32 v18, v18
	s_nop 0
	v_mul_f32_e32 v20, 0x45800000, v18
	v_cndmask_b32_e32 v18, v18, v20, vcc
	v_mov_b64_e32 v[20:21], s[30:31]
	v_mad_i64_i32 v[20:21], s[0:1], v19, s16, v[20:21]
	s_mov_b64 s[0:1], 0x1000
	s_nop 0
	v_lshl_add_u64 v[22:23], v[20:21], 0, s[0:1]
	v_lshl_add_u64 v[20:21], v[20:21], 0, v[78:79]
	v_lshl_add_u64 v[32:33], v[22:23], 0, v[78:79]
	v_lshl_add_u64 v[242:243], v[22:23], 0, v[78:79]
	global_load_dwordx4 v[152:155], v[48:49], off
	global_load_dwordx4 v[156:159], v[20:21], off
	global_load_dwordx4 v[160:163], v[242:243], off
	global_load_dwordx4 v[164:167], v[48:49], off offset:1024
	global_load_dwordx4 v[168:171], v[20:21], off offset:1024
	global_load_dwordx4 v[234:237], v[242:243], off offset:1024
	global_load_dwordx4 v[238:241], v[48:49], off offset:2048
	global_load_dwordx4 v[250:253], v[20:21], off offset:2048
	v_pk_mul_f32 v[14:15], v[14:15], v[18:19] op_sel_hi:[1,0]
	v_pk_mul_f32 v[10:11], v[10:11], v[18:19] op_sel_hi:[1,0]
	v_pk_mul_f32 v[12:13], v[12:13], v[18:19] op_sel_hi:[1,0]
	v_pk_mul_f32 v[6:7], v[6:7], v[18:19] op_sel_hi:[1,0]
	v_pk_mul_f32 v[8:9], v[8:9], v[18:19] op_sel_hi:[1,0]
	v_pk_mul_f32 v[2:3], v[2:3], v[18:19] op_sel_hi:[1,0]
	v_pk_mul_f32 v[4:5], v[4:5], v[18:19] op_sel_hi:[1,0]
	s_waitcnt vmcnt(8)
	s_waitcnt vmcnt(7)
	v_pk_mul_f32 v[14:15], v[152:153], v[14:15]
	s_waitcnt vmcnt(5)
	v_pk_add_f32 v[24:25], v[160:161], 1.0 op_sel_hi:[1,0]
	s_nop 0
	v_pk_fma_f32 v[14:15], v[24:25], v[14:15], v[156:157]
	s_nop 0
	v_cvt_pk_bf16_f32 v24, v14, v15
	v_pk_mul_f32 v[14:15], v[16:17], v[18:19] op_sel_hi:[1,0]
	v_pk_add_f32 v[16:17], v[162:163], 1.0 op_sel_hi:[1,0]
	v_pk_mul_f32 v[14:15], v[154:155], v[14:15]
	s_nop 0
	v_pk_fma_f32 v[14:15], v[14:15], v[16:17], v[158:159]
	v_lshl_add_u64 v[16:17], v[22:23], 0, v[76:77]
	v_cvt_pk_bf16_f32 v25, v14, v15
	v_lshl_add_u64 v[14:15], v[70:71], 1, v[50:51]
	global_store_dwordx2 v[14:15], v[24:25], off
	global_load_dwordx4 v[152:155], v[242:243], off offset:2048
	global_load_dwordx4 v[156:159], v[48:49], off offset:3072
	global_load_dwordx4 v[160:163], v[20:21], off offset:3072
	s_nop 0
	s_waitcnt vmcnt(8)
	v_pk_mul_f32 v[10:11], v[10:11], v[164:165]
	v_pk_mul_f32 v[12:13], v[12:13], v[166:167]
	s_waitcnt vmcnt(6)
	v_pk_add_f32 v[16:17], v[234:235], 1.0 op_sel_hi:[1,0]
	s_nop 0
	v_pk_fma_f32 v[10:11], v[10:11], v[16:17], v[168:169]
	v_pk_add_f32 v[16:17], v[236:237], 1.0 op_sel_hi:[1,0]
	v_cvt_pk_bf16_f32 v10, v10, v11
	v_pk_fma_f32 v[12:13], v[12:13], v[16:17], v[170:171]
	v_lshl_add_u64 v[16:17], v[22:23], 0, v[74:75]
	v_cvt_pk_bf16_f32 v11, v12, v13
	global_store_dwordx2 v[14:15], v[10:11], off offset:512
	global_load_dwordx4 v[164:167], v[242:243], off offset:3072
	s_nop 0
	v_lshl_add_u64 v[16:17], v[22:23], 0, v[72:73]
	s_waitcnt vmcnt(7)
	v_pk_mul_f32 v[6:7], v[6:7], v[238:239]
	v_pk_mul_f32 v[8:9], v[8:9], v[240:241]
	s_waitcnt vmcnt(4)
	v_pk_add_f32 v[10:11], v[152:153], 1.0 op_sel_hi:[1,0]
	s_nop 0
	v_pk_fma_f32 v[6:7], v[6:7], v[10:11], v[250:251]
	v_pk_add_f32 v[10:11], v[154:155], 1.0 op_sel_hi:[1,0]
	v_cvt_pk_bf16_f32 v6, v6, v7
	v_pk_fma_f32 v[8:9], v[8:9], v[10:11], v[252:253]
	s_nop 0
	v_cvt_pk_bf16_f32 v7, v8, v9
	global_store_dwordx2 v[14:15], v[6:7], off offset:1024
	s_nop 0
	s_nop 0
	s_waitcnt vmcnt(4)
	v_pk_mul_f32 v[2:3], v[2:3], v[156:157]
	v_pk_mul_f32 v[4:5], v[4:5], v[158:159]
	s_waitcnt vmcnt(1)
	v_pk_add_f32 v[6:7], v[164:165], 1.0 op_sel_hi:[1,0]
	s_nop 0
	v_pk_fma_f32 v[2:3], v[2:3], v[6:7], v[160:161]
	v_pk_add_f32 v[6:7], v[166:167], 1.0 op_sel_hi:[1,0]
	v_cvt_pk_bf16_f32 v2, v2, v3
	v_pk_fma_f32 v[4:5], v[4:5], v[6:7], v[162:163]
	s_nop 0
	v_cvt_pk_bf16_f32 v3, v4, v5
	global_store_dwordx2 v[14:15], v[2:3], off offset:1536
	s_branch .LBB0_164
